# attention PV ds_read double-buffering, ret_out staging loads issued up-front, MISC (dt/krope) projection tile skips its all-zero B half (loads+MFMAs)
# speedup vs baseline: 1.0126x; 1.0103x over previous
;     DI bool next(int i, Unit& u) const { if (!so.next(i, u)) return false; u.ak = (u.pn >= 4) ? 256 : 0; return true; }
;     DI bool next(int i, Unit& u) const { if (!so.next(i >> 2, u)) return false; u.sub = i & 3; u.ak = u.sub * 512; u.brow = u.sub * D + u.pn * BM; return true; }
; #define PG8_WAIT_V(n) asm volatile("s_waitcnt vmcnt(" #n ")" ::: "memory")
; #define PG8_BAR __builtin_amdgcn_s_barrier()
; template <class Epi, class Sched, bool ALIGN_EPI>
; DI void gemm_phase(LAS unsigned char* lds, const Gemm g, const Sched& Sc, const Epi& E, const int tid) {
;     const int wid = __builtin_amdgcn_readfirstlane(tid >> 6), lane = tid & 63, wr = wid >> 2, wc = wid & 3, fr = lane & 15, fq = lane >> 4;
;     const int K = g.K, nt = K / BK;
;     unsigned voffA[2], voffB[2];
; #pragma unroll
;     for (int i = 0; i < 2; ++i) { int R, C; stage_rc(tid * 16 + i * 8192, R, C); const int Rb = (R & ~31) + perm32(R & 31);
;         voffA[i] = (unsigned)(R * g.lda + C) * 2u; voffB[i] = (unsigned)(Rb * g.ldb + C) * 2u; }
;     const size_t kstep = (size_t)(BK * 2);
;     const size_t hA = (size_t)HALF * g.lda * 2, hB = (size_t)HALF * g.ldb * 2;
;     const unsigned ldsw = (unsigned)wid * 1024u;
;     const int aoff = lds_byte(wr * 64 + fr, fq * 8), boff = lds_byte(wc * 32 + fr, fq * 8);
;     ...
;     Unit cur, nxt; int ui = 0;
;     if (!Sc.next(0, cur)) return;
;     cur.ord = 0;
;     Acc acc;
; #pragma unroll
;     for (int a = 0; a < 2; ++a)
; #pragma unroll
;         for (int b = 0; b < 2; ++b)
; #pragma unroll
;             for (int m = 0; m < 4; ++m)
; #pragma unroll
;                 for (int n = 0; n < 2; ++n) acc[a][b][m][n] = (f32x4){0.f, 0.f, 0.f, 0.f};
;     bf16x8 At[4][2], B0[2][2], B1[2][2];
;     const char* cA = (const char*)g.A + ((size_t)cur.pm * BM * g.lda + cur.ak) * 2; const char* cB = (const char*)g.Bt + (size_t)cur.brow * g.ldb * 2;
;     PG8_STAGE(PG8_SB(0, 0), cB, voffB); PG8_STAGE(PG8_SB(0, 1), cB + hB, voffB); PG8_STAGE(PG8_SA(0, 0), cA, voffA); PG8_STAGE(PG8_SA(0, 1), cA + hA, voffA);
;     if (wr == 1) PG8_BAR;
;     PG8_WAIT_V(2); PG8_BAR;
;     PG8_STAGE(PG8_SB(1, 0), cB + kstep, voffB); PG8_STAGE(PG8_SA(1, 0), cA + kstep, voffA); PG8_STAGE(PG8_SB(1, 1), cB + hB + kstep, voffB);
;     PG8_WAIT_V(6); PG8_BAR;
.LBB0_661:
	v_ashrrev_i32_e32 v3, 31, v142
	v_lshrrev_b32_e32 v3, 26, v3
	v_add_u32_e32 v3, v142, v3
	v_ashrrev_i32_e32 v6, 6, v3
	v_bfe_i32 v3, v142, 27, 1
	v_lshlrev_b32_e32 v2, 4, v142
	v_lshrrev_b32_e32 v3, 22, v3
	v_add_u32_e32 v3, v2, v3
	v_and_b32_e32 v3, 0xfffffc00, v3
	v_sub_u32_e32 v3, v2, v3
	v_lshrrev_b32_e32 v4, 4, v3
	v_bitop3_b32 v3, v4, v3, 32 bitop3:0x6c
	v_ashrrev_i32_e32 v5, 31, v3
	v_lshrrev_b32_e32 v5, 26, v5
	v_add_u32_e32 v5, v3, v5
	v_lshlrev_b32_e32 v4, 3, v6
	v_ashrrev_i32_e32 v7, 6, v5
	v_and_b32_e32 v5, 0xc0, v5
	v_and_b32_e32 v4, -16, v4
	v_sub_u32_e32 v3, v3, v5
	v_add_u32_e32 v4, v7, v4
	v_lshlrev_b32_e32 v8, 5, v6
	v_ashrrev_i16_sdwa v3, v239, sext(v3) dst_sel:DWORD dst_unused:UNUSED_PAD src0_sel:DWORD src1_sel:BYTE_0
	v_and_b32_e32 v9, 32, v8
	v_bfe_i32 v8, v3, 0, 16
	v_lshlrev_b32_e32 v3, 1, v4
	v_lshrrev_b32_e32 v5, 2, v4
	v_and_b32_e32 v10, 3, v7
	s_mov_b32 s3, 0xfffe0
	v_and_b32_e32 v3, 24, v3
	v_and_b32_e32 v5, 4, v5
	v_and_or_b32 v10, v4, s3, v10
	v_or3_b32 v3, v10, v5, v3
	v_add_lshl_u32 v5, v9, v8, 1
	v_add_u32_e32 v2, 0x2000, v2
	v_lshl_add_u32 v132, v3, 12, v5
	v_ashrrev_i32_e32 v3, 31, v2
	v_lshrrev_b32_e32 v3, 22, v3
	v_add_u32_e32 v3, v2, v3
	v_ashrrev_i32_e32 v9, 10, v3
	v_mul_i32_i24_e32 v3, 0x400, v9
	v_readlane_b32 s12, v235, 32
	v_sub_u32_e32 v2, v2, v3
	v_readlane_b32 s13, v235, 33
	s_mul_i32 s20, s12, 0x1c80000
	v_lshrrev_b32_e32 v3, 4, v2
	s_lshl_b64 s[12:13], s[20:21], 1
	v_bitop3_b32 v2, v3, v2, 32 bitop3:0x6c
	s_add_u32 s23, s8, s12
	v_lshl_add_u32 v18, v4, 12, v5
	v_ashrrev_i32_e32 v4, 31, v2
	s_addc_u32 s26, s9, s13
	v_lshrrev_b32_e32 v4, 26, v4
	s_add_u32 s12, s23, 0x4000000
	v_lshlrev_b32_e32 v3, 3, v9
	v_add_u32_e32 v4, v2, v4
	s_addc_u32 s13, s26, 0
	v_and_b32_e32 v3, -16, v3
	v_ashrrev_i32_e32 v10, 6, v4
	s_add_i32 s16, s16, s2
	v_add_u32_e32 v3, v10, v3
	v_and_b32_e32 v12, 3, v10
	s_ashr_i32 s44, s30, 6
	s_ashr_i32 s17, s16, 31
	v_and_b32_e32 v4, 0xc0, v4
	v_and_or_b32 v12, v3, s3, v12
	s_lshl_b32 s51, s44, 10
	s_lshl_b64 s[2:3], s[16:17], 20
	s_add_i32 s17, s22, 0x10000
	v_sub_u32_e32 v2, v2, v4
	s_add_i32 s20, s17, s51
	s_ashr_i32 s27, s30, 8
	v_ashrrev_i16_sdwa v2, v239, sext(v2) dst_sel:DWORD dst_unused:UNUSED_PAD src0_sel:DWORD src1_sel:BYTE_0
	s_add_i32 s31, s20, 0x2000
	v_lshlrev_b32_e32 v5, 5, v9
	v_bfe_i32 v11, v2, 0, 16
	v_lshlrev_b32_e32 v2, 1, v3
	v_lshrrev_b32_e32 v4, 2, v3
	s_add_u32 s18, s23, 0x4080000
	v_and_b32_e32 v5, 32, v5
	v_and_b32_e32 v2, 24, v2
	v_and_b32_e32 v4, 4, v4
	s_addc_u32 s19, s26, 0
	s_add_i32 s36, s22, 0x14000
	v_or3_b32 v2, v12, v4, v2
	v_add_lshl_u32 v4, v5, v11, 1
	s_mov_b32 m0, s20
	s_add_i32 s37, s36, s51
	v_lshl_add_u32 v136, v2, 12, v4
	global_load_lds_dwordx4 v132, s[12:13]
	s_mov_b32 m0, s31
	s_add_i32 s38, s37, 0x2000
	global_load_lds_dwordx4 v136, s[12:13]
	s_add_u32 s41, s8, s2
	s_addc_u32 s42, s9, s3
	s_add_u32 s18, s41, 0x24300000
	s_addc_u32 s19, s42, 0
	s_add_i32 s39, s22, s51
	s_add_i32 s40, s39, 0x2000
	s_mov_b32 m0, s39
	s_add_u32 s46, s41, 0x24380000
	v_lshl_add_u32 v134, v3, 12, v4
	global_load_lds_dwordx4 v18, s[18:19]
	s_mov_b32 m0, s40
	s_addc_u32 s47, s42, 0
	s_add_i32 s41, s39, 0x4000
	global_load_lds_dwordx4 v134, s[18:19]
	s_mov_b32 m0, s41
	s_add_i32 s42, s39, 0x6000
	global_load_lds_dwordx4 v18, s[46:47]
	s_mov_b32 m0, s42
	v_mov_b32_e32 v135, v19
	global_load_lds_dwordx4 v134, s[46:47]
	v_lshl_add_u64 v[4:5], s[18:19], 0, v[18:19]
	s_cmp_lg_u32 s27, 1
	v_lshl_add_u64 v[2:3], s[18:19], 0, v[134:135]
	s_cbranch_scc1 .LBB0_663
	s_barrier
.LBB0_663:
	v_lshrrev_b32_e32 v12, 1, v142
	v_and_b32_e32 v144, 24, v12
	v_and_b32_e32 v145, 15, v142
	v_lshlrev_b32_e32 v12, 1, v144
	v_lshlrev_b32_e32 v13, 2, v142
	s_lshl_b32 s43, s27, 6
	v_lshl_or_b32 v12, v145, 6, v12
	s_lshl_b32 s27, s27, 13
	v_and_b32_e32 v13, 32, v13
	v_bitop3_b32 v14, v12, s27, v13 bitop3:0xde
	s_lshl_b32 s27, s44, 5
	s_and_b32 s44, s27, 0x60
	s_lshl_b32 s27, s44, 7
	s_add_u32 s48, s23, 0x4000080
	s_addc_u32 s49, s26, 0
	s_add_i32 s45, s22, 0x18000
	v_mov_b32_e32 v133, v19
	s_add_i32 s46, s45, s51
	v_mov_b32_e32 v137, v19
	v_bitop3_b32 v146, s27, v12, v13 bitop3:0xf6
	v_lshl_add_u64 v[12:13], s[48:49], 0, v[132:133]
	s_mov_b32 m0, s46
	s_waitcnt vmcnt(2)
	s_barrier
	global_load_lds_dwordx4 v[12:13], off
	v_lshl_add_u64 v[12:13], s[48:49], 0, v[136:137]
	s_add_i32 s47, s46, 0x2000
	s_add_i32 s48, s39, 0x8000
	s_add_i32 s49, s39, 0xa000
	s_mov_b32 m0, s47
	s_add_u32 s52, s23, 0x4080080
	global_load_lds_dwordx4 v[12:13], off
	v_lshl_add_u64 v[4:5], v[4:5], 0, s[60:61]
	s_mov_b32 m0, s48
	s_addc_u32 s53, s26, 0
	s_add_i32 s50, s22, 0x1c000
	global_load_lds_dwordx4 v[4:5], off
	v_lshl_add_u64 v[2:3], v[2:3], 0, s[60:61]
	s_mov_b32 m0, s49
	s_add_i32 s51, s50, s51
	global_load_lds_dwordx4 v[2:3], off
	v_lshl_add_u64 v[2:3], s[52:53], 0, v[132:133]
	v_readlane_b32 s26, v235, 20
	v_lshl_add_u64 v[2:3], s[52:53], 0, v[136:137]
	s_add_i32 s52, s51, 0x2000
	v_readlane_b32 s27, v235, 21
	s_add_u32 s53, s8, s26
	s_addc_u32 s54, s9, s27
	v_lshlrev_b32_e32 v2, 15, v9
	v_and_b32_e32 v2, 0xffff0000, v2
	s_add_u32 s55, s8, s2
	v_lshl_add_u32 v2, v10, 12, v2
	v_and_b32_e32 v3, 1, v9
	s_addc_u32 s56, s9, s3
	v_lshl_or_b32 v2, v3, 6, v2
	s_add_u32 s2, s55, 0x24380080
	v_lshl_add_u32 v2, v11, 1, v2
	v_mov_b32_e32 v3, v19
	s_addc_u32 s3, s56, 0
	v_lshl_add_u64 v[138:139], s[2:3], 0, v[2:3]
	v_lshlrev_b32_e32 v2, 15, v6
	v_and_b32_e32 v2, 0xffff0000, v2
	v_lshl_add_u32 v2, v7, 12, v2
	v_and_b32_e32 v3, 1, v6
	v_lshl_or_b32 v2, v3, 6, v2
	s_waitcnt vmcnt(4)
;     DI bool next(int i, Unit& u) const { if (!so.next(i, u)) return false; u.ak = (u.pn >= 4) ? 256 : 0; return true; }
;     DI bool next(int i, Unit& u) const { if (!so.next(i >> 2, u)) return false; u.sub = i & 3; u.ak = u.sub * 512; u.brow = u.sub * D + u.pn * BM; return true; }
; #define PG8_WAIT_V(n) asm volatile("s_waitcnt vmcnt(" #n ")" ::: "memory")
; #define PG8_WAIT_L(n) asm volatile("s_waitcnt lgkmcnt(" #n ")" ::: "memory")
; template <class Epi, class Sched, bool ALIGN_EPI>
; DI void gemm_phase(LAS unsigned char* lds, const Gemm g, const Sched& Sc, const Epi& E, const int tid) {
;     ...
;     Acc acc;
; #pragma unroll
;     for (int a = 0; a < 2; ++a)
; #pragma unroll
;         for (int b = 0; b < 2; ++b)
; #pragma unroll
;             for (int m = 0; m < 4; ++m)
; #pragma unroll
;                 for (int n = 0; n < 2; ++n) acc[a][b][m][n] = (f32x4){0.f, 0.f, 0.f, 0.f};
;     bf16x8 At[4][2], B0[2][2], B1[2][2];
;     const char* cA = (const char*)g.A + ((size_t)cur.pm * BM * g.lda + cur.ak) * 2; const char* cB = (const char*)g.Bt + (size_t)cur.brow * g.ldb * 2;
;     PG8_STAGE(PG8_SB(0, 0), cB, voffB); PG8_STAGE(PG8_SB(0, 1), cB + hB, voffB); PG8_STAGE(PG8_SA(0, 0), cA, voffA); PG8_STAGE(PG8_SA(0, 1), cA + hA, voffA);
;     if (wr == 1) PG8_BAR;
;     PG8_WAIT_V(2); PG8_BAR;
;     PG8_STAGE(PG8_SB(1, 0), cB + kstep, voffB); PG8_STAGE(PG8_SA(1, 0), cA + kstep, voffA); PG8_STAGE(PG8_SB(1, 1), cB + hB + kstep, voffB);
;     PG8_WAIT_V(6); PG8_BAR;
;     for (;;) {
;         const bool has_next = Sc.next(ui + 1, nxt); nxt.ord = ui + 1;
;         const char* nA = has_next ? (const char*)g.A + ((size_t)nxt.pm * BM * g.lda + nxt.ak) * 2 : cA; const char* nB = has_next ? (const char*)g.Bt + (size_t)nxt.brow * g.ldb * 2 : cB;
;         for (int t = 0; t < nt; t += 2) {
;             const bool last = (t == nt - 2);
;             const char* a1 = cA + (size_t)(t + 1) * kstep;
;             const char* a2 = last ? nA : cA + (size_t)(t + 2) * kstep; const char* b2 = last ? nB : cB + (size_t)(t + 2) * kstep;
;             const char* a3 = a2 + kstep; const char* b3 = b2 + kstep;
;             PG8_LDB(B0, 0, 0); PG8_LDB(B1, 0, 1); PG8_SCHED; PG8_LDA(At, 0, 0); PG8_STAGE(PG8_SA(1, 1), a1 + hA, voffA);
;             PG8_WAIT_V(8); PG8_WAIT_L(0); PG8_BAR; PG8_MMA(0, 0, At, B0); PG8_MMA(0, 1, At, B1); PG8_BAR; PG8_SCHED;
	v_lshl_add_u32 v2, v8, 1, v2
	v_mov_b32_e32 v3, v19
	v_lshl_add_u64 v[140:141], s[2:3], 0, v[2:3]
	v_mov_b32_e32 v2, 0
	v_or_b32_e32 v143, s43, v145
	s_mov_b32 s57, -2
	s_mov_b64 s[2:3], 0
	v_add_u32_e32 v147, s22, v14
	v_mov_b32_e32 v3, v2
	v_mov_b32_e32 v4, v2
	v_mov_b32_e32 v5, v2
	v_mov_b32_e32 v6, v2
	v_mov_b32_e32 v7, v2
	v_mov_b32_e32 v8, v2
	v_mov_b32_e32 v9, v2
	v_mov_b32_e32 v10, v2
	v_mov_b32_e32 v11, v2
	v_mov_b32_e32 v12, v2
	v_mov_b32_e32 v13, v2
	v_mov_b32_e32 v14, v2
	v_mov_b32_e32 v15, v2
	v_mov_b32_e32 v16, v2
	v_mov_b32_e32 v17, v2
	v_mov_b32_e32 v36, v2
	v_mov_b32_e32 v37, v2
	v_mov_b32_e32 v38, v2
	v_mov_b32_e32 v39, v2
	v_mov_b32_e32 v40, v2
	v_mov_b32_e32 v41, v2
	v_mov_b32_e32 v42, v2
	v_mov_b32_e32 v43, v2
	v_mov_b32_e32 v44, v2
	v_mov_b32_e32 v45, v2
	v_mov_b32_e32 v46, v2
	v_mov_b32_e32 v47, v2
	v_mov_b32_e32 v48, v2
	v_mov_b32_e32 v49, v2
	v_mov_b32_e32 v50, v2
	v_mov_b32_e32 v51, v2
	v_mov_b32_e32 v20, v2
	v_mov_b32_e32 v21, v2
	v_mov_b32_e32 v22, v2
	v_mov_b32_e32 v23, v2
	v_mov_b32_e32 v24, v2
	v_mov_b32_e32 v25, v2
	v_mov_b32_e32 v26, v2
	v_mov_b32_e32 v27, v2
	v_mov_b32_e32 v28, v2
	v_mov_b32_e32 v29, v2
	v_mov_b32_e32 v30, v2
	v_mov_b32_e32 v31, v2
	v_mov_b32_e32 v32, v2
	v_mov_b32_e32 v33, v2
	v_mov_b32_e32 v34, v2
	v_mov_b32_e32 v35, v2
	v_mov_b32_e32 v52, v2
	v_mov_b32_e32 v53, v2
	v_mov_b32_e32 v54, v2
	v_mov_b32_e32 v55, v2
	v_mov_b32_e32 v56, v2
	v_mov_b32_e32 v57, v2
	v_mov_b32_e32 v58, v2
	v_mov_b32_e32 v59, v2
	v_mov_b32_e32 v60, v2
	v_mov_b32_e32 v61, v2
	v_mov_b32_e32 v62, v2
	v_mov_b32_e32 v63, v2
	v_mov_b32_e32 v64, v2
	v_mov_b32_e32 v65, v2
	v_mov_b32_e32 v66, v2
	v_mov_b32_e32 v67, v2
	v_mov_b32_e32 v68, v2
	v_mov_b32_e32 v69, v2
	v_mov_b32_e32 v70, v2
	v_mov_b32_e32 v71, v2
	v_mov_b32_e32 v72, v2
	v_mov_b32_e32 v73, v2
	v_mov_b32_e32 v74, v2
	v_mov_b32_e32 v75, v2
	v_mov_b32_e32 v76, v2
	v_mov_b32_e32 v77, v2
	v_mov_b32_e32 v78, v2
	v_mov_b32_e32 v79, v2
	v_mov_b32_e32 v80, v2
	v_mov_b32_e32 v81, v2
	v_mov_b32_e32 v82, v2
	v_mov_b32_e32 v83, v2
	v_mov_b32_e32 v100, v2
	v_mov_b32_e32 v101, v2
	v_mov_b32_e32 v102, v2
	v_mov_b32_e32 v103, v2
	v_mov_b32_e32 v104, v2
	v_mov_b32_e32 v105, v2
	v_mov_b32_e32 v106, v2
	v_mov_b32_e32 v107, v2
	v_mov_b32_e32 v108, v2
	v_mov_b32_e32 v109, v2
	v_mov_b32_e32 v110, v2
	v_mov_b32_e32 v111, v2
	v_mov_b32_e32 v112, v2
	v_mov_b32_e32 v113, v2
	v_mov_b32_e32 v114, v2
	v_mov_b32_e32 v115, v2
	v_mov_b32_e32 v84, v2
	v_mov_b32_e32 v85, v2
	v_mov_b32_e32 v86, v2
	v_mov_b32_e32 v87, v2
	v_mov_b32_e32 v88, v2
	v_mov_b32_e32 v89, v2
	v_mov_b32_e32 v90, v2
	v_mov_b32_e32 v91, v2
	v_mov_b32_e32 v92, v2
	v_mov_b32_e32 v93, v2
	v_mov_b32_e32 v94, v2
	v_mov_b32_e32 v95, v2
	v_mov_b32_e32 v96, v2
	v_mov_b32_e32 v97, v2
	v_mov_b32_e32 v98, v2
	v_mov_b32_e32 v99, v2
	v_mov_b32_e32 v116, v2
	v_mov_b32_e32 v117, v2
	v_mov_b32_e32 v118, v2
	v_mov_b32_e32 v119, v2
	v_mov_b32_e32 v120, v2
	v_mov_b32_e32 v121, v2
	v_mov_b32_e32 v122, v2
	v_mov_b32_e32 v123, v2
	v_mov_b32_e32 v124, v2
	v_mov_b32_e32 v125, v2
	v_mov_b32_e32 v126, v2
	v_mov_b32_e32 v127, v2
	v_mov_b32_e32 v128, v2
	v_mov_b32_e32 v129, v2
	v_mov_b32_e32 v130, v2
	v_mov_b32_e32 v131, v2
	s_barrier
.LBB0_664:
	v_add_u32_e32 v160, s17, v146
	s_add_u32 s22, s55, s2
	ds_read_b128 v[148:151], v160
	ds_read_b128 v[152:155], v160 offset:1024
	ds_read_b128 v[156:159], v160 offset:2048
	ds_read_b128 v[160:163], v160 offset:3072
	s_addc_u32 s23, s56, s3
	s_add_u32 s22, s22, 0x24300100
	s_addc_u32 s23, s23, 0
	s_add_u32 s62, s53, s2
	s_addc_u32 s63, s54, s3
	s_cmpk_eq_i32 s2, 0xf00
	s_cselect_b32 s27, s19, s23
	s_cselect_b32 s26, s18, s22
	s_cselect_b32 s23, s13, s63
	s_cselect_b32 s22, s12, s62
	v_lshl_add_u64 v[198:199], v[140:141], 0, s[2:3]
	s_add_i32 m0, s39, 0xc000
	ds_read_b128 v[180:183], v147
	ds_read_b128 v[184:187], v147 offset:1024
	ds_read_b128 v[188:191], v147 offset:2048
	ds_read_b128 v[192:195], v147 offset:3072
	ds_read_b128 v[210:213], v147 offset:4096
	ds_read_b128 v[214:217], v147 offset:5120
	ds_read_b128 v[218:221], v147 offset:6144
	ds_read_b128 v[222:225], v147 offset:7168
	global_load_lds_dwordx4 v[198:199], off
	v_lshl_add_u64 v[198:199], v[138:139], 0, s[2:3]
	s_add_i32 m0, s39, 0xe000
	s_nop 0
	global_load_lds_dwordx4 v[198:199], off
	s_waitcnt vmcnt(6)
	s_waitcnt lgkmcnt(0)
	s_barrier
	s_setprio 1
	s_waitcnt lgkmcnt(0)
	v_mfma_f32_16x16x32_bf16 v[128:131], v[148:151], v[180:183], v[128:131]
	v_mfma_f32_16x16x32_bf16 v[124:127], v[156:159], v[180:183], v[124:127]
	v_mfma_f32_16x16x32_bf16 v[120:123], v[148:151], v[188:191], v[120:123]
	v_mfma_f32_16x16x32_bf16 v[116:119], v[156:159], v[188:191], v[116:119]
	v_mfma_f32_16x16x32_bf16 v[96:99], v[148:151], v[210:213], v[96:99]
	v_mfma_f32_16x16x32_bf16 v[92:95], v[156:159], v[210:213], v[92:95]
	v_mfma_f32_16x16x32_bf16 v[88:91], v[148:151], v[218:221], v[88:91]
	v_mfma_f32_16x16x32_bf16 v[84:87], v[156:159], v[218:221], v[84:87]
	v_mfma_f32_16x16x32_bf16 v[128:131], v[152:155], v[184:187], v[128:131]
	v_mfma_f32_16x16x32_bf16 v[124:127], v[160:163], v[184:187], v[124:127]
	v_mfma_f32_16x16x32_bf16 v[120:123], v[152:155], v[192:195], v[120:123]
	v_mfma_f32_16x16x32_bf16 v[116:119], v[160:163], v[192:195], v[116:119]
	v_mfma_f32_16x16x32_bf16 v[96:99], v[152:155], v[214:217], v[96:99]
	v_mfma_f32_16x16x32_bf16 v[92:95], v[160:163], v[214:217], v[92:95]
	v_mfma_f32_16x16x32_bf16 v[88:91], v[152:155], v[222:225], v[88:91]
	v_mfma_f32_16x16x32_bf16 v[84:87], v[160:163], v[222:225], v[84:87]
	s_setprio 0
	s_barrier
; #define PG8_STAGE(bufoff, gbase, voff) do { _Pragma("unroll") for (int _i = 0; _i < 2; ++_i) \
;         __builtin_amdgcn_global_load_lds((const unsigned*)((const char*)(gbase) + (voff)[_i]), (LAS unsigned*)(lds + (bufoff) + ldsw + _i * 8192), 16, 0, 0); } while (0)
; #define PG8_LDA(dst, b, h) do { _Pragma("unroll") for (int m = 0; m < 4; ++m) _Pragma("unroll") for (int k = 0; k < 2; ++k) dst[m][k] = *(const LAS bf16x8*)(lds + PG8_SA(b, h) + aoff + m * 2048 + k * 1024); } while (0)
; #define PG8_LDB(dst, b, h) do { _Pragma("unroll") for (int n = 0; n < 2; ++n) _Pragma("unroll") for (int k = 0; k < 2; ++k) dst[n][k] = *(const LAS bf16x8*)(lds + PG8_SB(b, h) + boff + n * 2048 + k * 1024); } while (0)
; #define PG8_MMA(ai, bj, At, Bt) do { __builtin_amdgcn_s_setprio(1); _Pragma("unroll") for (int m = 0; m < 4; ++m) _Pragma("unroll") for (int n = 0; n < 2; ++n) _Pragma("unroll") for (int k = 0; k < 2; ++k) \
;         acc[ai][bj][m][n] = __builtin_amdgcn_mfma_f32_16x16x32_bf16(Bt[n][k], At[m][k], acc[ai][bj][m][n], 0, 0, 0); __builtin_amdgcn_s_setprio(0); } while (0)
; #define PG8_WAIT_V(n) asm volatile("s_waitcnt vmcnt(" #n ")" ::: "memory")
; #define PG8_BAR __builtin_amdgcn_s_barrier()
; template <class Epi, class Sched, bool ALIGN_EPI>
; DI void gemm_phase(LAS unsigned char* lds, const Gemm g, const Sched& Sc, const Epi& E, const int tid) {
;     ...
;             PG8_LDB(B0, 0, 0); PG8_LDB(B1, 0, 1); PG8_SCHED; PG8_LDA(At, 0, 0); PG8_STAGE(PG8_SA(1, 1), a1 + hA, voffA);
;             PG8_WAIT_V(8); PG8_WAIT_L(0); PG8_BAR; PG8_MMA(0, 0, At, B0); PG8_MMA(0, 1, At, B1); PG8_BAR; PG8_SCHED;
;             PG8_LDA(At, 0, 1); PG8_STAGE(PG8_SB(0, 0), b2, voffB); PG8_STAGE(PG8_SB(0, 1), b2 + hB, voffB); PG8_STAGE(PG8_SA(0, 0), a2, voffA);
;             PG8_WAIT_V(8); PG8_WAIT_L(0); PG8_BAR; PG8_MMA(1, 0, At, B0); PG8_MMA(1, 1, At, B1); PG8_BAR; PG8_SCHED;
;             PG8_LDB(B0, 1, 0); PG8_LDB(B1, 1, 1); PG8_SCHED; PG8_LDA(At, 1, 0); PG8_STAGE(PG8_SA(0, 1), a2 + hA, voffA);
;             PG8_WAIT_V(8); PG8_WAIT_L(0); PG8_BAR; PG8_MMA(0, 0, At, B0); PG8_MMA(0, 1, At, B1); PG8_BAR; PG8_SCHED;
;             PG8_LDA(At, 1, 1); PG8_STAGE(PG8_SB(1, 0), b3, voffB); PG8_STAGE(PG8_SB(1, 1), b3 + hB, voffB); PG8_STAGE(PG8_SA(1, 0), a3, voffA);
;             PG8_WAIT_V(8); PG8_WAIT_L(0); PG8_BAR; PG8_MMA(1, 0, At, B0); PG8_MMA(1, 1, At, B1); PG8_BAR; PG8_SCHED;
;         }
	s_mov_b32 m0, s20
	v_lshl_add_u64 v[198:199], s[22:23], 0, v[132:133]
	s_add_u32 s62, s22, 0x80000
	ds_read_b128 v[180:183], v147 offset:16384
	ds_read_b128 v[184:187], v147 offset:17408
	ds_read_b128 v[188:191], v147 offset:18432
	ds_read_b128 v[192:195], v147 offset:19456
	ds_read_b128 v[210:213], v147 offset:20480
	ds_read_b128 v[214:217], v147 offset:21504
	ds_read_b128 v[218:221], v147 offset:22528
	ds_read_b128 v[222:225], v147 offset:23552
	global_load_lds_dwordx4 v[198:199], off
	v_lshl_add_u64 v[200:201], s[22:23], 0, v[136:137]
	s_mov_b32 m0, s31
	s_addc_u32 s63, s23, 0
	global_load_lds_dwordx4 v[200:201], off
	v_lshl_add_u64 v[226:227], s[62:63], 0, v[132:133]
	v_lshl_add_u64 v[228:229], s[26:27], 0, v[134:135]
	v_lshl_add_u64 v[226:227], s[62:63], 0, v[136:137]
	v_lshl_add_u64 v[226:227], s[26:27], 0, v[18:19]
	s_mov_b32 m0, s39
	s_nop 0
	global_load_lds_dwordx4 v[226:227], off
	s_mov_b32 m0, s40
	s_nop 0
	global_load_lds_dwordx4 v[228:229], off
	s_waitcnt vmcnt(6)
	s_waitcnt lgkmcnt(0)
	s_barrier
	s_setprio 1
	s_waitcnt lgkmcnt(0)
	v_mfma_f32_16x16x32_bf16 v[64:67], v[148:151], v[180:183], v[64:67]
	v_mfma_f32_16x16x32_bf16 v[60:63], v[156:159], v[180:183], v[60:63]
	v_mfma_f32_16x16x32_bf16 v[56:59], v[148:151], v[188:191], v[56:59]
	v_mfma_f32_16x16x32_bf16 v[52:55], v[156:159], v[188:191], v[52:55]
	v_mfma_f32_16x16x32_bf16 v[32:35], v[148:151], v[210:213], v[32:35]
	v_mfma_f32_16x16x32_bf16 v[28:31], v[156:159], v[210:213], v[28:31]
	v_mfma_f32_16x16x32_bf16 v[24:27], v[148:151], v[218:221], v[24:27]
	v_mfma_f32_16x16x32_bf16 v[20:23], v[156:159], v[218:221], v[20:23]
	v_mfma_f32_16x16x32_bf16 v[64:67], v[152:155], v[184:187], v[64:67]
	v_mfma_f32_16x16x32_bf16 v[60:63], v[160:163], v[184:187], v[60:63]
	v_mfma_f32_16x16x32_bf16 v[56:59], v[152:155], v[192:195], v[56:59]
	v_mfma_f32_16x16x32_bf16 v[52:55], v[160:163], v[192:195], v[52:55]
	v_mfma_f32_16x16x32_bf16 v[32:35], v[152:155], v[214:217], v[32:35]
	v_mfma_f32_16x16x32_bf16 v[28:31], v[160:163], v[214:217], v[28:31]
	v_mfma_f32_16x16x32_bf16 v[24:27], v[152:155], v[222:225], v[24:27]
	v_mfma_f32_16x16x32_bf16 v[20:23], v[160:163], v[222:225], v[20:23]
	s_setprio 0
	s_barrier
	v_add_u32_e32 v160, s45, v146
	ds_read_b128 v[148:151], v160
	ds_read_b128 v[152:155], v160 offset:1024
	ds_read_b128 v[156:159], v160 offset:2048
	ds_read_b128 v[160:163], v160 offset:3072
	s_add_u32 s26, s26, 0x80000
	s_addc_u32 s27, s27, 0
	s_mov_b32 m0, s41
	v_lshl_add_u64 v[230:231], s[26:27], 0, v[18:19]
	ds_read_b128 v[180:183], v147 offset:32768
	ds_read_b128 v[184:187], v147 offset:33792
	ds_read_b128 v[188:191], v147 offset:34816
	ds_read_b128 v[192:195], v147 offset:35840
	ds_read_b128 v[210:213], v147 offset:36864
	ds_read_b128 v[214:217], v147 offset:37888
	ds_read_b128 v[218:221], v147 offset:38912
	ds_read_b128 v[222:225], v147 offset:39936
	global_load_lds_dwordx4 v[230:231], off
	v_lshl_add_u64 v[230:231], s[26:27], 0, v[134:135]
	s_mov_b32 m0, s42
	s_nop 0
	global_load_lds_dwordx4 v[230:231], off
	s_waitcnt vmcnt(6)
	s_waitcnt lgkmcnt(0)
	s_barrier
	s_setprio 1
	s_waitcnt lgkmcnt(0)
	v_mfma_f32_16x16x32_bf16 v[128:131], v[148:151], v[180:183], v[128:131]
	v_mfma_f32_16x16x32_bf16 v[124:127], v[156:159], v[180:183], v[124:127]
	v_mfma_f32_16x16x32_bf16 v[120:123], v[148:151], v[188:191], v[120:123]
	v_mfma_f32_16x16x32_bf16 v[116:119], v[156:159], v[188:191], v[116:119]
	v_mfma_f32_16x16x32_bf16 v[96:99], v[148:151], v[210:213], v[96:99]
	v_mfma_f32_16x16x32_bf16 v[92:95], v[156:159], v[210:213], v[92:95]
	v_mfma_f32_16x16x32_bf16 v[88:91], v[148:151], v[218:221], v[88:91]
	v_mfma_f32_16x16x32_bf16 v[84:87], v[156:159], v[218:221], v[84:87]
	v_mfma_f32_16x16x32_bf16 v[128:131], v[152:155], v[184:187], v[128:131]
	v_mfma_f32_16x16x32_bf16 v[124:127], v[160:163], v[184:187], v[124:127]
	v_mfma_f32_16x16x32_bf16 v[120:123], v[152:155], v[192:195], v[120:123]
	v_mfma_f32_16x16x32_bf16 v[116:119], v[160:163], v[192:195], v[116:119]
	v_mfma_f32_16x16x32_bf16 v[96:99], v[152:155], v[214:217], v[96:99]
	v_mfma_f32_16x16x32_bf16 v[92:95], v[160:163], v[214:217], v[92:95]
	v_mfma_f32_16x16x32_bf16 v[88:91], v[152:155], v[222:225], v[88:91]
	v_mfma_f32_16x16x32_bf16 v[84:87], v[160:163], v[222:225], v[84:87]
	s_setprio 0
	s_barrier
	s_mov_b32 m0, s46
	v_lshl_add_u64 v[198:199], v[198:199], 0, s[60:61]
	s_add_u32 s22, s22, 0x80080
	ds_read_b128 v[180:183], v147 offset:49152
	ds_read_b128 v[184:187], v147 offset:50176
	ds_read_b128 v[188:191], v147 offset:51200
	ds_read_b128 v[192:195], v147 offset:52224
	ds_read_b128 v[210:213], v147 offset:53248
	ds_read_b128 v[214:217], v147 offset:54272
	ds_read_b128 v[218:221], v147 offset:55296
	ds_read_b128 v[222:225], v147 offset:56320
	global_load_lds_dwordx4 v[198:199], off
	v_lshl_add_u64 v[198:199], v[200:201], 0, s[60:61]
	s_mov_b32 m0, s47
	s_addc_u32 s23, s23, 0
	global_load_lds_dwordx4 v[198:199], off
	v_lshl_add_u64 v[198:199], s[22:23], 0, v[132:133]
	v_lshl_add_u64 v[198:199], s[22:23], 0, v[136:137]
	v_lshl_add_u64 v[198:199], v[226:227], 0, s[60:61]
	s_mov_b32 m0, s48
	s_nop 0
	global_load_lds_dwordx4 v[198:199], off
	v_lshl_add_u64 v[198:199], v[228:229], 0, s[60:61]
	s_mov_b32 m0, s49
	s_nop 0
	global_load_lds_dwordx4 v[198:199], off
	s_waitcnt vmcnt(6)
	s_waitcnt lgkmcnt(0)
	s_barrier
	s_setprio 1
	s_waitcnt lgkmcnt(0)
	v_mfma_f32_16x16x32_bf16 v[64:67], v[148:151], v[180:183], v[64:67]
	v_mfma_f32_16x16x32_bf16 v[60:63], v[156:159], v[180:183], v[60:63]
	v_mfma_f32_16x16x32_bf16 v[56:59], v[148:151], v[188:191], v[56:59]
	v_mfma_f32_16x16x32_bf16 v[52:55], v[156:159], v[188:191], v[52:55]
	v_mfma_f32_16x16x32_bf16 v[32:35], v[148:151], v[210:213], v[32:35]
	v_mfma_f32_16x16x32_bf16 v[28:31], v[156:159], v[210:213], v[28:31]
	v_mfma_f32_16x16x32_bf16 v[24:27], v[148:151], v[218:221], v[24:27]
	v_mfma_f32_16x16x32_bf16 v[20:23], v[156:159], v[218:221], v[20:23]
	v_mfma_f32_16x16x32_bf16 v[64:67], v[152:155], v[184:187], v[64:67]
	v_mfma_f32_16x16x32_bf16 v[60:63], v[160:163], v[184:187], v[60:63]
	v_mfma_f32_16x16x32_bf16 v[56:59], v[152:155], v[192:195], v[56:59]
	v_mfma_f32_16x16x32_bf16 v[52:55], v[160:163], v[192:195], v[52:55]
	v_mfma_f32_16x16x32_bf16 v[32:35], v[152:155], v[214:217], v[32:35]
	v_mfma_f32_16x16x32_bf16 v[28:31], v[160:163], v[214:217], v[28:31]
	v_mfma_f32_16x16x32_bf16 v[24:27], v[152:155], v[222:225], v[24:27]
	v_mfma_f32_16x16x32_bf16 v[20:23], v[160:163], v[222:225], v[20:23]
	s_setprio 0
	s_barrier
	s_add_i32 s57, s57, 2
	s_add_u32 s2, s2, 0x100
	s_addc_u32 s3, s3, 0
	s_cmp_gt_u32 s57, 29
	s_cbranch_scc0 .LBB0_664
	s_cmpk_lt_u32 s30, 0x100
	s_cbranch_scc0 .LBB0_667
	s_barrier

; DI unsigned pk2(float lo, float hi) { const f32x2 v = {lo, hi}; const bf16x2_t b = __builtin_convertvector(v, bf16x2_t); return __builtin_bit_cast(unsigned, b); }
; #define MFMA16(a, b, c) __builtin_amdgcn_mfma_f32_16x16x32_bf16((a), (b), (c), 0, 0, 0)
; #define AT_VLD(dst, db_) { _Pragma("unroll") for (int s2 = 0; s2 < 2; ++s2) { const LAS bf16* vp = Vs + ((db_) * 16 + lc) * 72 + 32 * s2 + 4 * g4; \
;                     const u32x2 v0 = *(const LAS u32x2*)vp, v1 = *(const LAS u32x2*)(vp + 16); const u32x4 vw = (u32x4){v0.x, v0.y, v1.x, v1.y}; dst[s2] = __builtin_bit_cast(bf16x8, vw); } }
; DI void u_attn2(Frame& F, int h, int qb, int sp, int ntile) {
;     ...
;                 for (int s2 = 0; s2 < 2; ++s2) { u32x4 pw; pw.x = pk2(p[8 * s2], p[8 * s2 + 1]); pw.y = pk2(p[8 * s2 + 2], p[8 * s2 + 3]); pw.z = pk2(p[8 * s2 + 4], p[8 * s2 + 5]); pw.w = pk2(p[8 * s2 + 6], p[8 * s2 + 7]); pf[qq][s2] = __builtin_bit_cast(bf16x8, pw); }
;             }
;             {
;                 bf16x8 vfr[2][2];
;     ...
;                 AT_VLD(vfr[0], 0)
; #pragma unroll
;                 for (int db = 0; db < 8; ++db) {
;                     if (db < 7) AT_VLD(vfr[(db + 1) & 1], db + 1)
; #pragma unroll
;                     for (int s2 = 0; s2 < 2; ++s2)
; #pragma unroll
;                         for (int qq = 0; qq < 2; ++qq) o[db][qq] = MFMA16(vfr[db & 1][s2], pf[qq][s2], o[db][qq]);
;                 }
;     ...
;             }
.LBB0_2235:
	v_cvt_pk_bf16_f32 v142, v142, v143
	v_cvt_pk_bf16_f32 v143, v144, v145
	v_cvt_pk_bf16_f32 v145, v140, v141
	v_add_u32_e32 v140, 0x6000, v189
	v_cvt_pk_bf16_f32 v198, v192, v194
	v_cvt_pk_bf16_f32 v200, v193, v195
	v_cvt_pk_bf16_f32 v192, v211, v212
	v_cvt_pk_bf16_f32 v193, v213, v214
	v_cvt_pk_bf16_f32 v212, v146, v147
	v_cvt_pk_bf16_f32 v213, v148, v149
	ds_read2_b64 v[146:149], v140 offset0:128 offset1:132
	ds_read2_b64 v[244:247], v140 offset0:136 offset1:140
	v_cvt_pk_bf16_f32 v199, v164, v191
	v_cvt_pk_bf16_f32 v201, v203, v210
	v_cvt_pk_bf16_f32 v210, v162, v218
	v_cvt_pk_bf16_f32 v211, v150, v151
	v_add_u32_e32 v219, 0x6000, v188
	v_add_u32_e32 v140, 0x6800, v189
	ds_read2_b64 v[220:223], v219 offset0:128 offset1:132
	ds_read2_b64 v[224:227], v219 offset0:136 offset1:140
	s_waitcnt lgkmcnt(3)
	v_mfma_f32_16x16x32_bf16 v[106:109], v[146:149], v[198:201], v[106:109]
	v_cvt_pk_bf16_f32 v194, v215, v217
	v_cvt_pk_bf16_f32 v195, v156, v157
	v_cvt_pk_bf16_f32 v144, v152, v153
	v_mfma_f32_16x16x32_bf16 v[102:105], v[146:149], v[210:213], v[102:105]
	ds_read2_b64 v[146:149], v140 offset0:160 offset1:164
	s_waitcnt lgkmcnt(3)
	v_mfma_f32_16x16x32_bf16 v[106:109], v[244:247], v[192:195], v[106:109]
	v_add_f32_e32 v138, v138, v139
	v_mfma_f32_16x16x32_bf16 v[102:105], v[244:247], v[142:145], v[102:105]
	ds_read2_b64 v[244:247], v140 offset0:168 offset1:172
	v_fmac_f32_e32 v138, v163, v20
	v_add_f32_e32 v20, v154, v155
	v_add_u32_e32 v140, 0x7000, v189
	s_waitcnt lgkmcnt(1)
	v_mfma_f32_16x16x32_bf16 v[98:101], v[146:149], v[198:201], v[98:101]
	v_fmac_f32_e32 v20, v165, v18
	v_mov_b32_e32 v165, v20
	v_mov_b32_e32 v163, v138
	v_mfma_f32_16x16x32_bf16 v[94:97], v[146:149], v[210:213], v[94:97]
	ds_read2_b64 v[146:149], v140 offset0:192 offset1:196
	v_mov_b32_e32 v164, v21
	s_waitcnt lgkmcnt(1)
	v_mfma_f32_16x16x32_bf16 v[98:101], v[244:247], v[192:195], v[98:101]
	v_mov_b32_e32 v162, v216
	v_mfma_f32_16x16x32_bf16 v[94:97], v[244:247], v[142:145], v[94:97]
	ds_read2_b64 v[244:247], v140 offset0:200 offset1:204
	v_add_u32_e32 v140, 0x8800, v190
	s_waitcnt lgkmcnt(1)
	v_mfma_f32_16x16x32_bf16 v[90:93], v[146:149], v[198:201], v[90:93]
	v_mfma_f32_16x16x32_bf16 v[86:89], v[146:149], v[210:213], v[86:89]
	ds_read2_b64 v[146:149], v140 offset1:4
	s_waitcnt lgkmcnt(1)
	v_mfma_f32_16x16x32_bf16 v[90:93], v[244:247], v[192:195], v[90:93]
	v_mfma_f32_16x16x32_bf16 v[86:89], v[244:247], v[142:145], v[86:89]
	ds_read2_b64 v[244:247], v140 offset0:8 offset1:12
	v_add_u32_e32 v140, 0x9000, v190
	s_waitcnt lgkmcnt(1)
	v_mfma_f32_16x16x32_bf16 v[82:85], v[146:149], v[198:201], v[82:85]
	v_mfma_f32_16x16x32_bf16 v[78:81], v[146:149], v[210:213], v[78:81]
	ds_read2_b64 v[146:149], v140 offset0:32 offset1:36
	s_waitcnt lgkmcnt(1)
	v_mfma_f32_16x16x32_bf16 v[82:85], v[244:247], v[192:195], v[82:85]
	v_mfma_f32_16x16x32_bf16 v[78:81], v[244:247], v[142:145], v[78:81]
	ds_read2_b64 v[244:247], v140 offset0:40 offset1:44
	v_add_u32_e32 v140, 0x9800, v190
	s_waitcnt lgkmcnt(1)
	v_mfma_f32_16x16x32_bf16 v[70:73], v[146:149], v[198:201], v[70:73]
	v_mfma_f32_16x16x32_bf16 v[74:77], v[146:149], v[210:213], v[74:77]
	ds_read2_b64 v[146:149], v140 offset0:64 offset1:68
	s_waitcnt lgkmcnt(1)
	v_mfma_f32_16x16x32_bf16 v[70:73], v[244:247], v[192:195], v[70:73]
	v_mfma_f32_16x16x32_bf16 v[74:77], v[244:247], v[142:145], v[74:77]
	ds_read2_b64 v[244:247], v140 offset0:72 offset1:76
	v_add_u32_e32 v140, 0xa000, v190
	s_waitcnt lgkmcnt(1)
	v_mfma_f32_16x16x32_bf16 v[66:69], v[146:149], v[198:201], v[66:69]
	v_mfma_f32_16x16x32_bf16 v[58:61], v[146:149], v[210:213], v[58:61]
	ds_read2_b64 v[146:149], v140 offset0:96 offset1:100
	ds_read2_b64 v[150:153], v140 offset0:104 offset1:108
	s_waitcnt lgkmcnt(2)
	v_mfma_f32_16x16x32_bf16 v[66:69], v[244:247], v[192:195], v[66:69]
	v_mfma_f32_16x16x32_bf16 v[58:61], v[244:247], v[142:145], v[58:61]
	v_mfma_f32_16x16x32_bf16 v[134:137], v[220:223], v[198:201], v[134:137]
	v_mfma_f32_16x16x32_bf16 v[118:121], v[220:223], v[210:213], v[118:121]
	s_waitcnt lgkmcnt(1)
	v_mfma_f32_16x16x32_bf16 v[54:57], v[146:149], v[198:201], v[54:57]
	v_mfma_f32_16x16x32_bf16 v[62:65], v[146:149], v[210:213], v[62:65]
	v_mfma_f32_16x16x32_bf16 v[134:137], v[224:227], v[192:195], v[134:137]
	v_mfma_f32_16x16x32_bf16 v[118:121], v[224:227], v[142:145], v[118:121]
	s_waitcnt lgkmcnt(0)
	v_mfma_f32_16x16x32_bf16 v[54:57], v[150:153], v[192:195], v[54:57]
	v_mfma_f32_16x16x32_bf16 v[62:65], v[150:153], v[142:145], v[62:65]

; #define GAS __attribute__((address_space(1)))
; #define LAS __attribute__((address_space(3)))
; DI unsigned f2bf(float f) { const __bf16 b = (__bf16)f; return (unsigned)__builtin_bit_cast(unsigned short, b); }
; DI void u_ret_out(Frame& F, int l_, int c, int h) {
;     ...
;     { StG gq, gk, gv; stage_ld(gq, (const bf16*)(ws + WS_QR) + rowb, 512, 64, 16, tid); stage_ld(gk, (const bf16*)(ws + WS_KR) + rowb, 512, 64, 16, tid); stage_ld(gv, (const bf16*)(ws + WS_VR) + rowb, 512, 64, 16, tid);
;       stage_st_nat(gq, Qs, 136, 64, 16, tid); stage_st_nat(gk, Ks, 136, 64, 16, tid); stage_st_tr(gv, Vt, 72, 64, 16, tid); }
;     { const float* sp = (const float*)(ws + WS_RKV) + ((size_t)(c * 4 + h) * 128) * 128;
;       for (int p = tid; p < 4096; p += NTHR) { const int d = p >> 5, e0 = (p & 31) * 4; const f32x4 v = *(const GAS f32x4*)(sp + (size_t)d * 128 + e0);
;           LAS bf16* q = St + e0 * 136 + d; q[0] = (bf16)f2bf(v.x); q[136] = (bf16)f2bf(v.y); q[272] = (bf16)f2bf(v.z); q[408] = (bf16)f2bf(v.w); } }
.LBB0_2353:
	v_mov_b32_e32 v6, v3
	s_lshl_b32 s3, s2, 4
	v_ashrrev_i32_e32 v2, 31, v6
	v_lshrrev_b32_e32 v2, 28, v2
	v_add_u32_e32 v2, v6, v2
	v_ashrrev_i32_e32 v4, 4, v2
	v_ashrrev_i32_e32 v5, 31, v4
	s_and_b32 s16, s3, 0xffffffc0
	v_lshlrev_b64 v[16:17], 10, v[4:5]
	v_add_u32_e32 v5, 0x200, v6
	s_and_b32 s20, s2, 3
	s_ashr_i32 s17, s16, 31
	v_ashrrev_i32_e32 v7, 31, v5
	s_lshl_b64 s[18:19], s[16:17], 10
	s_lshl_b32 s3, s20, 8
	v_and_b32_e32 v2, -16, v2
	v_lshrrev_b32_e32 v7, 28, v7
	s_or_b32 s3, s18, s3
	v_sub_u32_e32 v2, v6, v2
	v_add_u32_e32 v7, v5, v7
	s_add_u32 s22, s25, s3
	v_lshlrev_b32_e32 v10, 3, v2
	v_ashrrev_i32_e32 v30, 4, v7
	v_and_b32_e32 v7, -16, v7
	s_addc_u32 s23, s30, s19
	v_ashrrev_i32_e32 v11, 31, v10
	v_sub_u32_e32 v7, v5, v7
	v_ashrrev_i32_e32 v31, 31, v30
	v_lshl_add_u64 v[8:9], s[22:23], 0, v[16:17]
	v_lshlrev_b64 v[28:29], 1, v[10:11]
	v_lshlrev_b64 v[32:33], 10, v[30:31]
	v_lshlrev_b32_e32 v14, 3, v7
	v_lshl_add_u64 v[8:9], v[8:9], 0, v[28:29]
	v_lshl_add_u64 v[12:13], s[22:23], 0, v[32:33]
	v_ashrrev_i32_e32 v15, 31, v14
	s_add_u32 s22, s31, s3
	global_load_dwordx4 v[8:11], v[8:9], off
	v_lshlrev_b64 v[34:35], 1, v[14:15]
	s_addc_u32 s23, s36, s19
	v_lshl_add_u64 v[12:13], v[12:13], 0, v[34:35]
	v_lshl_add_u64 v[20:21], s[22:23], 0, v[16:17]
	global_load_dwordx4 v[12:15], v[12:13], off
	v_lshl_add_u64 v[20:21], v[20:21], 0, v[28:29]
	v_lshl_add_u64 v[24:25], s[22:23], 0, v[32:33]
	global_load_dwordx4 v[20:23], v[20:21], off
	v_lshl_add_u64 v[24:25], v[24:25], 0, v[34:35]
	global_load_dwordx4 v[24:27], v[24:25], off
	v_mul_lo_u32 v18, v4, s94
	v_lshlrev_b32_e32 v2, 4, v2
	s_add_u32 s18, s37, s3
	v_add3_u32 v2, s24, v18, v2
	s_addc_u32 s19, s38, s19
	v_lshlrev_b32_e32 v7, 4, v7
	v_lshl_add_u64 v[16:17], s[18:19], 0, v[16:17]
	v_lshl_add_u64 v[16:17], v[16:17], 0, v[28:29]
	v_lshl_add_u64 v[28:29], s[18:19], 0, v[32:33]
	v_lshl_add_u64 v[28:29], v[28:29], 0, v[34:35]
	global_load_dwordx4 v[70:73], v[16:17], off
	global_load_dwordx4 v[74:77], v[28:29], off
	s_ashr_i32 s3, s2, 31
	s_lshl_b64 s[22:23], s[2:3], 16
	s_add_u32 s22, s39, s22
	s_addc_u32 s23, s40, s23
	v_ashrrev_i32_e32 v110, 5, v6
	v_lshlrev_b32_e32 v111, 2, v6
	v_and_b32_e32 v111, 0x7c, v111
	v_lshlrev_b32_e32 v112, 9, v110
	v_lshl_add_u32 v112, v111, 2, v112
	v_mul_u32_u24_e32 v111, 0x110, v111
	v_lshlrev_b32_e32 v110, 1, v110
	v_add3_u32 v113, s24, v111, v110
	global_load_dwordx4 v[78:81], v112, s[22:23]
	v_add_u32_e32 v112, 0x2000, v112
	global_load_dwordx4 v[82:85], v112, s[22:23]
	v_add_u32_e32 v112, 0x2000, v112
	global_load_dwordx4 v[86:89], v112, s[22:23]
	v_add_u32_e32 v112, 0x2000, v112
	global_load_dwordx4 v[90:93], v112, s[22:23]
	v_add_u32_e32 v112, 0x2000, v112
	global_load_dwordx4 v[94:97], v112, s[22:23]
	v_add_u32_e32 v112, 0x2000, v112
	global_load_dwordx4 v[98:101], v112, s[22:23]
	v_add_u32_e32 v112, 0x2000, v112
	global_load_dwordx4 v[102:105], v112, s[22:23]
	v_add_u32_e32 v112, 0x2000, v112
	global_load_dwordx4 v[106:109], v112, s[22:23]
	s_movk_i32 s3, 0x1000
	v_cmp_gt_i32_e32 vcc, s3, v6
	s_waitcnt vmcnt(10)
	ds_write_b128 v2, v[8:11]
	v_mul_lo_u32 v8, v30, s94
	v_add3_u32 v7, s24, v8, v7
	ds_write_b128 v7, v[12:15]
	ds_write_b128 v2, v[20:23] offset:17408
	ds_write_b128 v7, v[24:27] offset:17408
	v_lshlrev_b32_e32 v2, 7, v4
	v_lshlrev_b32_e32 v7, 3, v6
	v_sub_u32_e32 v2, v7, v2
	v_mul_lo_u32 v2, v2, s90
	v_lshlrev_b32_e32 v4, 1, v4
	v_add3_u32 v2, s24, v2, v4
	v_lshlrev_b32_e32 v4, 3, v5
	s_waitcnt vmcnt(9)
	ds_write_b16 v2, v70 offset:34816
	ds_write_b16_d16_hi v2, v70 offset:34960
	ds_write_b16 v2, v71 offset:35104
	ds_write_b16_d16_hi v2, v71 offset:35248
	ds_write_b16 v2, v72 offset:35392
	ds_write_b16_d16_hi v2, v72 offset:35536
	ds_write_b16 v2, v73 offset:35680
	ds_write_b16_d16_hi v2, v73 offset:35824
	v_lshlrev_b32_e32 v2, 7, v30
	v_sub_u32_e32 v2, v4, v2
	v_mul_lo_u32 v2, v2, s90
	v_lshlrev_b32_e32 v4, 1, v30
	v_add3_u32 v2, s24, v2, v4
	s_waitcnt vmcnt(8)
	ds_write_b16 v2, v74 offset:34816
	ds_write_b16_d16_hi v2, v74 offset:34960
	ds_write_b16 v2, v75 offset:35104
	ds_write_b16_d16_hi v2, v75 offset:35248
	ds_write_b16 v2, v76 offset:35392
	ds_write_b16_d16_hi v2, v76 offset:35536
	ds_write_b16 v2, v77 offset:35680
	ds_write_b16_d16_hi v2, v77 offset:35824
	s_and_saveexec_b64 s[18:19], vcc
	s_cbranch_execz .LBB0_2352
	s_waitcnt vmcnt(7)
	v_cvt_pk_bf16_f32 v7, v78, s0
	v_cvt_pk_bf16_f32 v8, v79, s0
	v_cvt_pk_bf16_f32 v9, v80, s0
	v_cvt_pk_bf16_f32 v10, v81, s0
	ds_write_b16 v113, v7 offset:53248
	ds_write_b16 v113, v8 offset:53520
	ds_write_b16 v113, v9 offset:53792
	ds_write_b16 v113, v10 offset:54064
	s_waitcnt vmcnt(6)
	v_cvt_pk_bf16_f32 v7, v82, s0
	v_cvt_pk_bf16_f32 v8, v83, s0
	v_cvt_pk_bf16_f32 v9, v84, s0
	v_cvt_pk_bf16_f32 v10, v85, s0
	ds_write_b16 v113, v7 offset:53280
	ds_write_b16 v113, v8 offset:53552
	ds_write_b16 v113, v9 offset:53824
	ds_write_b16 v113, v10 offset:54096
	s_waitcnt vmcnt(5)
	v_cvt_pk_bf16_f32 v7, v86, s0
	v_cvt_pk_bf16_f32 v8, v87, s0
	v_cvt_pk_bf16_f32 v9, v88, s0
	v_cvt_pk_bf16_f32 v10, v89, s0
	ds_write_b16 v113, v7 offset:53312
	ds_write_b16 v113, v8 offset:53584
	ds_write_b16 v113, v9 offset:53856
	ds_write_b16 v113, v10 offset:54128
	s_waitcnt vmcnt(4)
	v_cvt_pk_bf16_f32 v7, v90, s0
	v_cvt_pk_bf16_f32 v8, v91, s0
	v_cvt_pk_bf16_f32 v9, v92, s0
	v_cvt_pk_bf16_f32 v10, v93, s0
	ds_write_b16 v113, v7 offset:53344
	ds_write_b16 v113, v8 offset:53616
	ds_write_b16 v113, v9 offset:53888
	ds_write_b16 v113, v10 offset:54160
	s_waitcnt vmcnt(3)
	v_cvt_pk_bf16_f32 v7, v94, s0
	v_cvt_pk_bf16_f32 v8, v95, s0
	v_cvt_pk_bf16_f32 v9, v96, s0
	v_cvt_pk_bf16_f32 v10, v97, s0
	ds_write_b16 v113, v7 offset:53376
	ds_write_b16 v113, v8 offset:53648
	ds_write_b16 v113, v9 offset:53920
	ds_write_b16 v113, v10 offset:54192
	s_waitcnt vmcnt(2)
	v_cvt_pk_bf16_f32 v7, v98, s0
	v_cvt_pk_bf16_f32 v8, v99, s0
	v_cvt_pk_bf16_f32 v9, v100, s0
	v_cvt_pk_bf16_f32 v10, v101, s0
	ds_write_b16 v113, v7 offset:53408
	ds_write_b16 v113, v8 offset:53680
	ds_write_b16 v113, v9 offset:53952
	ds_write_b16 v113, v10 offset:54224
	s_waitcnt vmcnt(1)
	v_cvt_pk_bf16_f32 v7, v102, s0
	v_cvt_pk_bf16_f32 v8, v103, s0
	v_cvt_pk_bf16_f32 v9, v104, s0
	v_cvt_pk_bf16_f32 v10, v105, s0
	ds_write_b16 v113, v7 offset:53440
	ds_write_b16 v113, v8 offset:53712
	ds_write_b16 v113, v9 offset:53984
	ds_write_b16 v113, v10 offset:54256
	s_waitcnt vmcnt(0)
	v_cvt_pk_bf16_f32 v7, v106, s0
	v_cvt_pk_bf16_f32 v8, v107, s0
	v_cvt_pk_bf16_f32 v9, v108, s0
	v_cvt_pk_bf16_f32 v10, v109, s0
	ds_write_b16 v113, v7 offset:53472
	ds_write_b16 v113, v8 offset:53744
	ds_write_b16 v113, v9 offset:54016
	ds_write_b16 v113, v10 offset:54288
	s_branch .LBB0_2352
